# placement trial: MLA tile loop alone shifted by 16 bytes (later loops unchanged)
# speedup vs baseline: 1.0050x; 1.0011x over previous
; DI float xhalf_sum(float m) { auto rr = __builtin_amdgcn_permlane32_swap(__float_as_uint(m), __float_as_uint(m), false, false); return __uint_as_float(rr[0]) + __uint_as_float(rr[1]); }
; template <int DQK, int DV, bool CAUSAL, int KT, bool PRIO>
; DI void attn_unit(const bf16_t* Qb, int qpitch, const bf16_t* Kb, int kpitch, const bf16_t* Vtb, int vpitch, bf16_t* Ob, int opitch, int q0, int nt, LAS unsigned char* lds, float kbound, const float* qgain, const int* qpos, float qscale) {
;     ...
;         float q2 = 0.f;
; #pragma unroll
;         for (int ks = 0; ks < DQK / 16; ++ks)
; #pragma unroll
;             for (int e = 0; e < 8; ++e) { const float v = __uint_as_float(((unsigned)(unsigned short)qf[ks][e]) << 16); q2 += v * v; }
;         q2 = xhalf_sum(q2);
;         nomax = __all(sqrtf(q2) * kbound <= 100.0f) != 0;
.LBB0_1486:
	s_waitcnt vmcnt(0) lgkmcnt(0)
	v_and_b32_e32 v9, 0xffff0000, v116
	v_lshlrev_b32_e32 v8, 16, v116
	v_mul_f32_e32 v11, v9, v9
	v_fmac_f32_e32 v11, v8, v8
	v_lshlrev_b32_e32 v8, 16, v117
	v_fmac_f32_e32 v11, v8, v8
	v_and_b32_e32 v8, 0xffff0000, v117
	v_fmac_f32_e32 v11, v8, v8
	v_lshlrev_b32_e32 v8, 16, v118
	v_fmac_f32_e32 v11, v8, v8
	v_and_b32_e32 v8, 0xffff0000, v118
	v_fmac_f32_e32 v11, v8, v8
	v_lshlrev_b32_e32 v8, 16, v119
	v_fmac_f32_e32 v11, v8, v8
	v_and_b32_e32 v8, 0xffff0000, v119
	v_fmac_f32_e32 v11, v8, v8
	v_lshlrev_b32_e32 v8, 16, v120
	v_fmac_f32_e32 v11, v8, v8
	v_and_b32_e32 v8, 0xffff0000, v120
	v_fmac_f32_e32 v11, v8, v8
	v_lshlrev_b32_e32 v8, 16, v121
	v_fmac_f32_e32 v11, v8, v8
	v_and_b32_e32 v8, 0xffff0000, v121
	v_fmac_f32_e32 v11, v8, v8
	v_lshlrev_b32_e32 v8, 16, v122
	v_fmac_f32_e32 v11, v8, v8
	v_and_b32_e32 v8, 0xffff0000, v122
	v_fmac_f32_e32 v11, v8, v8
	v_lshlrev_b32_e32 v8, 16, v123
	v_fmac_f32_e32 v11, v8, v8
	v_and_b32_e32 v8, 0xffff0000, v123
	v_fmac_f32_e32 v11, v8, v8
	v_lshlrev_b32_e32 v8, 16, v124
	v_fmac_f32_e32 v11, v8, v8
	v_and_b32_e32 v8, 0xffff0000, v124
	v_fmac_f32_e32 v11, v8, v8
	v_lshlrev_b32_e32 v8, 16, v125
	v_fmac_f32_e32 v11, v8, v8
	v_and_b32_e32 v8, 0xffff0000, v125
	v_fmac_f32_e32 v11, v8, v8
	v_lshlrev_b32_e32 v8, 16, v126
	v_fmac_f32_e32 v11, v8, v8
	v_and_b32_e32 v8, 0xffff0000, v126
	v_fmac_f32_e32 v11, v8, v8
	v_lshlrev_b32_e32 v8, 16, v127
	v_fmac_f32_e32 v11, v8, v8
	v_and_b32_e32 v8, 0xffff0000, v127
	v_fmac_f32_e32 v11, v8, v8
	v_lshlrev_b32_e32 v8, 16, v128
	v_fmac_f32_e32 v11, v8, v8
	v_and_b32_e32 v8, 0xffff0000, v128
	v_fmac_f32_e32 v11, v8, v8
	v_lshlrev_b32_e32 v8, 16, v129
	v_fmac_f32_e32 v11, v8, v8
	v_and_b32_e32 v8, 0xffff0000, v129
	v_fmac_f32_e32 v11, v8, v8
	v_lshlrev_b32_e32 v8, 16, v130
	v_fmac_f32_e32 v11, v8, v8
	v_and_b32_e32 v8, 0xffff0000, v130
	v_fmac_f32_e32 v11, v8, v8
	v_lshlrev_b32_e32 v8, 16, v131
	v_fmac_f32_e32 v11, v8, v8
	v_and_b32_e32 v8, 0xffff0000, v131
	v_fmac_f32_e32 v11, v8, v8
	v_lshlrev_b32_e32 v8, 16, v132
	v_fmac_f32_e32 v11, v8, v8
	v_and_b32_e32 v8, 0xffff0000, v132
	v_fmac_f32_e32 v11, v8, v8
	v_lshlrev_b32_e32 v8, 16, v133
	v_fmac_f32_e32 v11, v8, v8
	v_and_b32_e32 v8, 0xffff0000, v133
	v_fmac_f32_e32 v11, v8, v8
	v_lshlrev_b32_e32 v8, 16, v134
	v_fmac_f32_e32 v11, v8, v8
	v_and_b32_e32 v8, 0xffff0000, v134
	v_fmac_f32_e32 v11, v8, v8
	v_lshlrev_b32_e32 v8, 16, v135
	v_fmac_f32_e32 v11, v8, v8
	v_and_b32_e32 v8, 0xffff0000, v135
	v_fmac_f32_e32 v11, v8, v8
	v_lshlrev_b32_e32 v8, 16, v136
	v_fmac_f32_e32 v11, v8, v8
	v_and_b32_e32 v8, 0xffff0000, v136
	v_fmac_f32_e32 v11, v8, v8
	v_and_b32_e32 v9, 0xffff0000, v137
	v_lshlrev_b32_e32 v8, 16, v137
	v_pk_mul_f32 v[8:9], v[8:9], v[8:9]
	s_xor_b64 s[34:35], s[2:3], -1
	v_add_f32_e32 v8, v8, v11
	v_add_f32_e32 v11, v9, v8
	v_and_b32_e32 v9, 0xffff0000, v138
	v_lshlrev_b32_e32 v8, 16, v138
	v_pk_mul_f32 v[8:9], v[8:9], v[8:9]
	v_mad_i64_i32 v[2:3], s[2:3], v149, s88, 0
	v_add_f32_e32 v8, v8, v11
	v_add_f32_e32 v11, v9, v8
	v_and_b32_e32 v9, 0xffff0000, v139
	v_lshlrev_b32_e32 v8, 16, v139
	v_pk_mul_f32 v[8:9], v[8:9], v[8:9]
	v_mad_i64_i32 v[4:5], s[2:3], v151, s88, 0
	v_add_f32_e32 v8, v8, v11
	v_add_f32_e32 v8, v9, v8
	v_mov_b32_e32 v9, v8
	s_nop 1
	v_permlane32_swap_b32_e32 v8, v9
	v_add_f32_e32 v8, v8, v9
	v_mul_f32_e32 v9, 0x4f800000, v8
	v_cmp_gt_f32_e32 vcc, s91, v8
	v_mad_i64_i32 v[6:7], s[2:3], v153, s88, 0
	s_nop 0
	v_cndmask_b32_e32 v8, v8, v9, vcc
	v_sqrt_f32_e32 v9, v8
	s_add_i32 s2, s38, 0x100
	s_lshr_b32 s68, s2, 7
	v_mul_lo_u32 v178, v149, s53
	v_add_u32_e32 v11, -1, v9
	v_fma_f32 v12, -v11, v9, v8
	v_cmp_ge_f32_e64 s[2:3], 0, v12
; DI float xhalf_sum(float m) { auto rr = __builtin_amdgcn_permlane32_swap(__float_as_uint(m), __float_as_uint(m), false, false); return __uint_as_float(rr[0]) + __uint_as_float(rr[1]); }
; template <int DQK, int DV, bool CAUSAL, int KT, bool PRIO>
; DI void attn_unit(const bf16_t* Qb, int qpitch, const bf16_t* Kb, int kpitch, const bf16_t* Vtb, int vpitch, bf16_t* Ob, int opitch, int q0, int nt, LAS unsigned char* lds, float kbound, const float* qgain, const int* qpos, float qscale) {
;     ...
;     f32x16 o[DV / 32], negm;
; #pragma unroll
;     for (int i = 0; i < 16; ++i) negm[i] = 0.f;
; #pragma unroll
;     for (int d = 0; d < DV / 32; ++d)
; #pragma unroll
;         for (int i = 0; i < 16; ++i) o[d][i] = 0.f;
;     float mrun = 0.f, lrun = 0.f; bool first = true;
;     bool nomax = false;
;     if (PRIO) {
;         float q2 = 0.f;
; #pragma unroll
;         for (int ks = 0; ks < DQK / 16; ++ks)
; #pragma unroll
;             for (int e = 0; e < 8; ++e) { const float v = __uint_as_float(((unsigned)(unsigned short)qf[ks][e]) << 16); q2 += v * v; }
;         q2 = xhalf_sum(q2);
;         nomax = __all(sqrtf(q2) * kbound <= 100.0f) != 0;
;     }
;     lstore(0);
;     __syncthreads();
;     const int qabs = q0 + 32 * w + r, qlo = q0 + 32 * w;
	v_add_u32_e32 v12, 1, v9
	v_lshlrev_b32_e32 v179, 4, v150
	v_cndmask_b32_e64 v11, v9, v11, s[2:3]
	v_fma_f32 v9, -v12, v9, v8
	v_cmp_lt_f32_e64 s[2:3], 0, v9
	v_mul_lo_u32 v181, v151, s53
	v_lshlrev_b32_e32 v182, 4, v152
	v_cndmask_b32_e64 v9, v11, v12, s[2:3]
	v_mul_f32_e32 v11, 0x37800000, v9
	v_cndmask_b32_e32 v9, v9, v11, vcc
	v_cmp_class_f32_e32 vcc, v8, v176
	v_mul_lo_u32 v183, v153, s53
	v_lshlrev_b32_e32 v184, 4, v154
	v_cndmask_b32_e32 v8, v9, v8, vcc
	v_mul_f32_e32 v8, v174, v8
	v_cmp_ge_f32_e32 vcc, s52, v8
	v_add3_u32 v8, 0, v178, v179
	ds_write_b128 v8, v[96:99]
	v_add3_u32 v8, 0, v181, v182
	ds_write_b128 v8, v[100:103]
	v_add3_u32 v8, 0, v183, v184
	v_mul_lo_u32 v185, v68, s56
	ds_write_b128 v8, v[104:107]
	v_add_u32_e32 v8, 0, v185
	v_and_b32_e32 v186, 1, v69
	v_lshlrev_b32_e32 v186, 3, v186
	v_sub_u32_e32 v186, 0, v186
	v_lshl_add_u32 v186, v69, 4, v186
	v_add3_u32 v8, v8, v186, s57
	v_mul_lo_u32 v187, v74, s56
	ds_write2_b64 v8, v[108:109], v[110:111] offset1:2
	v_add_u32_e32 v8, 0, v187
	v_and_b32_e32 v188, 1, v75
	v_lshlrev_b32_e32 v188, 3, v188
	v_sub_u32_e32 v188, 0, v188
	v_lshl_add_u32 v188, v75, 4, v188
	v_and_b32_e32 v10, 31, v155
	v_add3_u32 v8, v8, v188, s57
	s_ashr_i32 s27, s26, 31
	s_and_b32 s69, s39, 0xffffffe0
	ds_write2_b64 v8, v[112:113], v[114:115] offset1:2
	v_mul_u32_u24_e32 v8, 0x110, v10
	s_cmp_lg_u64 vcc, exec
	v_add3_u32 v191, v0, v8, v0
	v_lshl_add_u64 v[8:9], s[22:23], 0, v[70:71]
	s_cselect_b64 s[2:3], -1, 0
	s_add_i32 s69, s69, s38
	v_lshl_add_u64 v[164:165], v[72:73], 1, v[8:9]
	v_lshl_add_u64 v[8:9], s[22:23], 0, v[64:65]
	v_lshl_add_u64 v[6:7], s[24:25], 0, v[6:7]
	v_lshl_add_u64 v[4:5], s[24:25], 0, v[4:5]
	v_lshl_add_u64 v[2:3], s[24:25], 0, v[2:3]
	v_mov_b32_e32 v14, v1
	v_mov_b32_e32 v15, v1
	v_or_b32_e32 v189, s69, v10
	v_mul_u32_u24_e32 v192, 0xd0, v10
	v_lshl_add_u64 v[166:167], v[66:67], 1, v[8:9]
	v_lshl_add_u64 v[168:169], v[62:63], 1, v[6:7]
	v_lshl_add_u64 v[170:171], v[60:61], 1, v[4:5]
	v_lshl_add_u64 v[172:173], v[58:59], 1, v[2:3]
	v_lshl_add_u64 v[164:165], s[4:5], 0, v[164:165]
	v_lshl_add_u64 v[166:167], s[4:5], 0, v[166:167]
	v_lshl_add_u64 v[168:169], s[4:5], 0, v[168:169]
	v_lshl_add_u64 v[170:171], s[4:5], 0, v[170:171]
	v_lshl_add_u64 v[172:173], s[4:5], 0, v[172:173]
	s_nop 0
	s_nop 0
	s_nop 0
	s_nop 0
	s_nop 0
	s_nop 0
	s_nop 0
	s_nop 0
	s_nop 0
	s_nop 0
	v_mov_b32_e32 v0, v1
	v_mov_b32_e32 v2, v1
	v_mov_b32_e32 v3, v1
	v_mov_b32_e32 v4, v1
	v_mov_b32_e32 v5, v1
	v_mov_b32_e32 v6, v1
	v_mov_b32_e32 v7, v1
	v_mov_b32_e32 v8, v1
	v_mov_b32_e32 v9, v1
	v_mov_b32_e32 v10, v1
	v_mov_b32_e32 v11, v1
	v_mov_b32_e32 v12, v1
	v_mov_b32_e32 v13, v1
	v_mov_b64_e32 v[30:31], v[14:15]
	v_mov_b64_e32 v[46:47], v[14:15]
	v_mov_b64_e32 v[62:63], v[14:15]
	s_mov_b32 s12, 0
	s_or_b32 s70, s69, 31
	v_lshl_add_u32 v190, v148, 4, 0
	v_lshlrev_b32_e32 v180, 2, v148
	s_mov_b64 s[40:41], -1
	v_mov_b32_e32 v193, 0
	s_mov_b32 s71, 63
	v_mov_b64_e32 v[28:29], v[12:13]
	v_mov_b64_e32 v[26:27], v[10:11]
	v_mov_b64_e32 v[24:25], v[8:9]
	v_mov_b64_e32 v[22:23], v[6:7]
	v_mov_b64_e32 v[20:21], v[4:5]
	v_mov_b64_e32 v[18:19], v[2:3]
	v_mov_b64_e32 v[16:17], v[0:1]
	v_mov_b64_e32 v[44:45], v[12:13]
	v_mov_b64_e32 v[42:43], v[10:11]
	v_mov_b64_e32 v[40:41], v[8:9]
	v_mov_b64_e32 v[38:39], v[6:7]
	v_mov_b64_e32 v[36:37], v[4:5]
	v_mov_b64_e32 v[34:35], v[2:3]
	v_mov_b64_e32 v[32:33], v[0:1]
	v_mov_b64_e32 v[60:61], v[12:13]
	v_mov_b64_e32 v[58:59], v[10:11]
	v_mov_b64_e32 v[56:57], v[8:9]
	v_mov_b64_e32 v[54:55], v[6:7]
	v_mov_b64_e32 v[52:53], v[4:5]
	v_mov_b64_e32 v[50:51], v[2:3]
	v_mov_b64_e32 v[48:49], v[0:1]
	v_mov_b32_e32 v0, 0
	s_waitcnt lgkmcnt(0)
	s_barrier

; #define LAS __attribute__((address_space(3)))
; template <int DQK, int DV, bool CAUSAL, int KT, bool PRIO>
; DI void attn_unit(const bf16_t* Qb, int qpitch, const bf16_t* Kb, int kpitch, const bf16_t* Vtb, int vpitch, bf16_t* Ob, int opitch, int q0, int nt, LAS unsigned char* lds, float kbound, const float* qgain, const int* qpos, float qscale) {
;     ...
;     auto lstore = [&](int buf) {
; #pragma unroll
;         for (int i = 0; i < NKR; ++i) { const int c = tid + i * 512; if (NKC % 512 == 0 || c < NKC) *(LAS u32x4*)(lds + buf * KBUF + (c / KCH) * KS + (c % KCH) * 16) = kreg[i]; }
; #pragma unroll
;         for (int i = 0; i < NVR; ++i) { const int c = tid + i * 512; LAS unsigned char* p = lds + VOFF + buf * VBUF + (c / VCH) * VS + (c % VCH) * 16;
;             *(LAS u32x2*)p = (u32x2){vreg[i].x, vreg[i].y}; *(LAS u32x2*)(p + 8) = (u32x2){vreg[i].z, vreg[i].w}; }
;     ...
;                     float ps = 0.f;
; #pragma unroll
;                     for (int i = 0; i < 16; ++i) { s0[i] = __builtin_amdgcn_exp2f(s0[i]); ps += s0[i]; asm volatile("" : "+v"(ps)); }
; #pragma unroll
;                     for (int i = 0; i < 16; ++i) { s1[i] = __builtin_amdgcn_exp2f(s1[i]); ps += s1[i]; asm volatile("" : "+v"(ps)); }
;                     lrun += ps;
;                     bf16x8 pf[4];
; #pragma unroll
;                     for (int sf = 0; sf < 2; ++sf) {
;                         u32x4 pw; pw.x = pk2(s0[8 * sf], s0[8 * sf + 1]); pw.y = pk2(s0[8 * sf + 2], s0[8 * sf + 3]); pw.z = pk2(s0[8 * sf + 4], s0[8 * sf + 5]); pw.w = pk2(s0[8 * sf + 6], s0[8 * sf + 7]); pf[sf] = __builtin_bit_cast(bf16x8, pw);
;                         u32x4 pv; pv.x = pk2(s1[8 * sf], s1[8 * sf + 1]); pv.y = pk2(s1[8 * sf + 2], s1[8 * sf + 3]); pv.z = pk2(s1[8 * sf + 4], s1[8 * sf + 5]); pv.w = pk2(s1[8 * sf + 6], s1[8 * sf + 7]); pf[2 + sf] = __builtin_bit_cast(bf16x8, pv);
;                     }
;                     __builtin_amdgcn_sched_barrier(0); __builtin_amdgcn_s_setprio(1); __builtin_amdgcn_sched_barrier(0);
; #pragma unroll
;                     for (int q4 = 0; q4 < 4; ++q4)
; #pragma unroll
;                         for (int d = 0; d < NDB; ++d) o[d] = MFMA32(vf[q4][d], pf[q4], o[d]);
;                     __builtin_amdgcn_sched_barrier(0); __builtin_amdgcn_s_setprio(0); __builtin_amdgcn_sched_barrier(0);
.LBB0_1514:
	s_nop 7
	v_exp_f32_e32 v14, v80
	v_exp_f32_e32 v15, v81
	v_exp_f32_e32 v80, v82
	v_exp_f32_e32 v81, v83
	v_add_f32_e32 v82, 0, v14
	v_exp_f32_e32 v83, v84
	v_add_f32_e32 v82, v15, v82
	v_exp_f32_e32 v84, v85
	v_add_f32_e32 v82, v80, v82
	v_exp_f32_e32 v85, v86
	v_add_f32_e32 v82, v81, v82
	v_exp_f32_e32 v86, v87
	v_add_f32_e32 v82, v83, v82
	v_exp_f32_e32 v87, v88
	v_add_f32_e32 v82, v84, v82
	v_exp_f32_e32 v88, v89
	v_add_f32_e32 v82, v85, v82
	v_exp_f32_e32 v89, v90
	v_add_f32_e32 v82, v86, v82
	v_exp_f32_e32 v90, v91
	v_add_f32_e32 v82, v87, v82
	v_exp_f32_e32 v91, v92
	v_add_f32_e32 v82, v88, v82
	v_exp_f32_e32 v92, v93
	v_add_f32_e32 v82, v89, v82
	v_exp_f32_e32 v93, v94
	v_add_f32_e32 v82, v90, v82
	v_exp_f32_e32 v94, v95
	v_add_f32_e32 v82, v91, v82
	v_exp_f32_e32 v95, v64
	v_add_f32_e32 v82, v92, v82
	v_exp_f32_e32 v194, v66
	v_add_f32_e32 v82, v93, v82
	v_exp_f32_e32 v195, v67
	v_add_f32_e32 v64, v94, v82
	v_exp_f32_e32 v82, v65
	v_exp_f32_e32 v197, v68
	v_add_f32_e32 v64, v95, v64
	v_exp_f32_e32 v198, v69
	v_add_f32_e32 v64, v82, v64
	v_exp_f32_e32 v199, v70
	v_add_f32_e32 v64, v194, v64
	v_exp_f32_e32 v71, v71
	v_add_f32_e32 v64, v195, v64
	v_exp_f32_e32 v200, v72
	v_add_f32_e32 v64, v197, v64
	v_exp_f32_e32 v201, v73
	v_add_f32_e32 v64, v198, v64
	v_exp_f32_e32 v202, v74
	v_add_f32_e32 v64, v199, v64
	v_exp_f32_e32 v203, v75
	v_add_f32_e32 v64, v71, v64
	v_exp_f32_e32 v204, v76
	v_add_f32_e32 v64, v200, v64
	v_exp_f32_e32 v205, v77
	v_add_f32_e32 v64, v201, v64
	v_exp_f32_e32 v206, v78
	v_add_f32_e32 v64, v202, v64
	v_exp_f32_e32 v79, v79
	v_add_f32_e32 v64, v203, v64
	v_cvt_pk_bf16_f32 v65, v80, v81
	v_add_f32_e32 v64, v204, v64
	v_cvt_pk_bf16_f32 v66, v83, v84
	v_add_f32_e32 v64, v205, v64
	v_cvt_pk_bf16_f32 v67, v85, v86
	v_add_f32_e32 v64, v206, v64
	v_cvt_pk_bf16_f32 v68, v95, v82
	v_add_f32_e32 v207, v79, v64
	v_cvt_pk_bf16_f32 v64, v14, v15
	v_cvt_pk_bf16_f32 v69, v194, v195
	v_cvt_pk_bf16_f32 v70, v197, v198
	v_cvt_pk_bf16_f32 v71, v199, v71
	v_cvt_pk_bf16_f32 v72, v87, v88
	v_cvt_pk_bf16_f32 v73, v89, v90
	v_cvt_pk_bf16_f32 v74, v91, v92
	v_cvt_pk_bf16_f32 v75, v93, v94
	v_cvt_pk_bf16_f32 v76, v200, v201
	v_cvt_pk_bf16_f32 v77, v202, v203
	v_cvt_pk_bf16_f32 v78, v204, v205
	v_cvt_pk_bf16_f32 v79, v206, v79
	s_setprio 1
	s_waitcnt lgkmcnt(0)
	s_waitcnt vmcnt(0)
	v_mfma_f32_32x32x16_bf16 v[32:47], v[156:159], v[64:67], v[32:47]
	v_add_f32_e32 v0, v0, v207
	s_xor_b32 s100, s75, 1
	s_mul_i32 s101, s100, 0x6800
	v_add3_u32 v250, s101, v178, v179
	v_mfma_f32_32x32x16_bf16 v[16:31], v[152:155], v[64:67], v[16:31]
	ds_write_b128 v250, v[96:99]
	v_add3_u32 v251, s101, v181, v182
	s_mulk_i32 s100, 0xdc00
	v_mfma_f32_32x32x16_bf16 v[32:47], v[140:143], v[72:75], v[32:47]
	ds_write_b128 v251, v[100:103]
	v_add3_u32 v250, s101, v183, v184
	s_add_i32 s101, s101, s100
	v_mfma_f32_32x32x16_bf16 v[16:31], v[148:151], v[72:75], v[16:31]
	ds_write_b128 v250, v[104:107]
	v_add_u32_e32 v251, s101, v185
	v_add3_u32 v251, v251, v186, s57
	v_mfma_f32_32x32x16_bf16 v[32:47], v[144:147], v[68:71], v[32:47]
	ds_write2_b64 v251, v[108:109], v[110:111] offset1:2
	v_add_u32_e32 v250, s101, v187
	v_add3_u32 v250, v250, v188, s57
	v_mfma_f32_32x32x16_bf16 v[16:31], v[10:13], v[68:71], v[16:31]
	ds_write2_b64 v250, v[112:113], v[114:115] offset1:2
	v_mfma_f32_32x32x16_bf16 v[32:47], v[6:9], v[76:79], v[32:47]
	v_mfma_f32_32x32x16_bf16 v[16:31], v[2:5], v[76:79], v[16:31]
	s_setprio 0
	s_branch .LBB0_1493
	s_nop 0
	s_nop 0
	s_nop 0
	s_nop 0
	s_nop 0
	s_nop 0
	s_nop 0
	s_nop 0
	s_nop 0
.LBB0_1515:
	s_branch .LBB0_1503
